# P1: bf16 copy of p (prompt rows) done by the one-unit workgroups only (two passes each) when the grid is 256; two-unit workgroups skip it
# speedup vs baseline: 1.0125x; 1.0052x over previous
; __device__ __forceinline__ unsigned pk2(float lo, float hi) { unsigned r; asm("v_cvt_pk_bf16_f32 %0, %1, %2" : "=v"(r) : "v"(lo), "v"(hi)); return r; }
; #define GIN(i) GPTR(const float, args.in[i])
; __global__ void __launch_bounds__(NWAVES * 64, 2) hymba_fwd(Args args) {
;     ...
;             { int tid = threadIdx.x; asm volatile("" : "+v"(tid));
;               const int e0 = bx * (NWAVES * 64) + tid, NE = G * NWAVES * 64;
;               const float* __restrict__ pp = GIN(I_PP) + (size_t)L * MP * PLE; bf16* __restrict__ pbo = PB;
; #pragma unroll 4
;               for (int e = e0; e < MP * (PLE / 8); e += NE) { const f32x4 a = *(const f32x4*)(pp + (size_t)e * 8), c = *(const f32x4*)(pp + (size_t)e * 8 + 4);
;                   v4u o; o.x = pk2(a[0], a[1]); o.y = pk2(a[2], a[3]); o.z = pk2(c[0], c[1]); o.w = pk2(c[2], c[3]); *(v4u*)(pbo + (size_t)e * 8) = o; }
.LBB0_674:
	v_mov_b32_e32 v2, v0
	v_readlane_b32 s68, v252, 10
	v_readlane_b32 s76, v252, 18
	v_add_u32_e32 v4, s67, v2
	v_readlane_b32 s77, v252, 19
	s_mov_b32 s0, 0x80000
	s_cmpk_lg_i32 s51, 0x100
	s_cbranch_scc1 .Lpc_keep
	s_cmpk_ge_i32 s56, 0x80
	s_cselect_b32 s0, s0, 0
.Lpc_keep:
	s_mov_b64 s[16:17], s[76:77]
	v_cmp_gt_i32_e32 vcc, s0, v4
	v_ashrrev_i32_e32 v5, 31, v4
	v_readlane_b32 s69, v252, 11
	v_readlane_b32 s70, v252, 12
	v_readlane_b32 s71, v252, 13
	v_readlane_b32 s72, v252, 14
	v_readlane_b32 s73, v252, 15
	v_readlane_b32 s74, v252, 16
	v_readlane_b32 s75, v252, 17
	v_readlane_b32 s78, v252, 20
	v_readlane_b32 s79, v252, 21
	v_readlane_b32 s80, v252, 22
	v_readlane_b32 s81, v252, 23
	v_readlane_b32 s82, v252, 24
	v_readlane_b32 s83, v252, 25
	s_and_saveexec_b64 s[0:1], vcc
	s_cbranch_execz .LBB0_677
	v_readlane_b32 s4, v253, 45
	v_readlane_b32 s5, v253, 46
	s_add_u32 s4, s16, s4
	s_addc_u32 s5, s17, s5
	v_lshlrev_b64 v[6:7], 5, v[4:5]
	v_lshl_add_u64 v[6:7], s[4:5], 0, v[6:7]
	v_readlane_b32 s4, v254, 26
	v_readlane_b32 s5, v254, 27
	v_lshl_add_u64 v[6:7], v[6:7], 0, 16
	s_mov_b64 s[16:17], 0
	v_lshl_add_u64 v[8:9], v[4:5], 4, s[4:5]
	v_mov_b32_e32 v2, v4
.LBB0_676:
	s_cmp_lg_u32 s92, 0x20000
	s_cbranch_scc1 .Lpconv_loop
	global_load_dwordx4 v[10:13], v[6:7], off offset:-16
	global_load_dwordx4 v[14:17], v[6:7], off
	v_lshl_add_u64 v[6:7], v[6:7], 0, s[90:91]
	global_load_dwordx4 v[108:111], v[6:7], off offset:-16
	global_load_dwordx4 v[112:115], v[6:7], off
	v_lshl_add_u64 v[6:7], v[6:7], 0, s[90:91]
	global_load_dwordx4 v[116:119], v[6:7], off offset:-16
	global_load_dwordx4 v[120:123], v[6:7], off
	v_lshl_add_u64 v[6:7], v[6:7], 0, s[90:91]
	global_load_dwordx4 v[124:127], v[6:7], off offset:-16
	global_load_dwordx4 v[128:131], v[6:7], off
	s_waitcnt vmcnt(6)
	v_cvt_pk_bf16_f32 v10, v10, v11
	v_cvt_pk_bf16_f32 v11, v12, v13
	v_cvt_pk_bf16_f32 v12, v14, v15
	v_cvt_pk_bf16_f32 v13, v16, v17
	global_store_dwordx4 v[8:9], v[10:13], off
	v_lshl_add_u64 v[8:9], v[8:9], 0, s[28:29]
	s_waitcnt vmcnt(5)
	v_cvt_pk_bf16_f32 v108, v108, v109
	v_cvt_pk_bf16_f32 v109, v110, v111
	v_cvt_pk_bf16_f32 v110, v112, v113
	v_cvt_pk_bf16_f32 v111, v114, v115
	global_store_dwordx4 v[8:9], v[108:111], off
	v_lshl_add_u64 v[8:9], v[8:9], 0, s[28:29]
	s_waitcnt vmcnt(4)
	v_cvt_pk_bf16_f32 v116, v116, v117
	v_cvt_pk_bf16_f32 v117, v118, v119
	v_cvt_pk_bf16_f32 v118, v120, v121
	v_cvt_pk_bf16_f32 v119, v122, v123
	global_store_dwordx4 v[8:9], v[116:119], off
	v_lshl_add_u64 v[8:9], v[8:9], 0, s[28:29]
	s_waitcnt vmcnt(3)
	v_cvt_pk_bf16_f32 v124, v124, v125
	v_cvt_pk_bf16_f32 v125, v126, v127
	v_cvt_pk_bf16_f32 v126, v128, v129
	v_cvt_pk_bf16_f32 v127, v130, v131
	global_store_dwordx4 v[8:9], v[124:127], off
	s_cmpk_lg_i32 s51, 0x100
	s_cbranch_scc1 .LBB0_677
	s_add_i32 s16, s16, 1
	s_cmp_lg_u32 s16, 1
	s_cbranch_scc1 .LBB0_677
	s_mov_b32 s4, 0xff200000
	s_mov_b32 s5, -1
	v_lshl_add_u64 v[6:7], v[6:7], 0, s[4:5]
	s_mov_b32 s4, 0xff900000
	v_lshl_add_u64 v[8:9], v[8:9], 0, s[4:5]
	s_branch .LBB0_676
